# norm phase: next row pair prefetched (8 x dwordx4) before the gates GEMV, consumed at next iteration top
# speedup vs baseline: 1.0052x; 1.0052x over previous
; __device__ void norm_phase(const Params& p, int layer, int which, int nrows, char* smem) {
;     ...
;   for (int pr = blockIdx.x * 8 + wid; pr < nrows / 2; pr += gridDim.x * 8) {
;     const int row0 = pr * 2;
;     const bool latent = row0 < NLAT;
;     const float* src;
;     if (which == 0 && layer == 0) src = latent ? p.x + (size_t)row0 * DM : p.ctx + (size_t)(row0 - NLAT) * DM;
;     else src = latent ? p.out + (size_t)row0 * DM : p.xcw + (size_t)(row0 - NLAT) * DM;
;     const int bidx = latent ? (row0 >> 11) : 16;
;     const float* shift = p.modv + ((size_t)(layer * 17 + bidx) * 6 + (which == 0 ? 0 : 3)) * DM;
;     const float* scale = shift + DM;
;     f32x4 v[2][4];
.LBB0_72:
	s_or_b64 exec, exec, s[0:1]
	v_readlane_b32 s0, v254, 32
	v_readlane_b32 s1, v254, 33
	s_xor_b64 s[24:25], s[0:1], -1
	v_readlane_b32 s0, v254, 34
	v_ashrrev_i32_e32 v2, 6, v4
	v_readlane_b32 s0, v252, 48
	v_readlane_b32 s1, v254, 35
	s_lshl_b32 s28, s96, 10
	v_add_u32_e32 v35, s0, v2
	s_movk_i32 s0, 0x4800
	s_mov_b32 s29, s1
	s_mul_i32 s56, s96, 17
	v_cmp_gt_i32_e32 vcc, s0, v35
	s_waitcnt lgkmcnt(0)
	s_barrier
	s_and_saveexec_b64 s[2:3], vcc
	s_cbranch_execz .LBB0_91
	v_cmp_lt_i32_e32 vcc, v246, v245
	v_readlane_b32 s4, v252, 16
	s_lshl_b64 s[0:1], s[28:29], 2
	v_cndmask_b32_e32 v0, v243, v246, vcc
	v_cmp_lt_i32_e32 vcc, v247, v245
	v_readlane_b32 s16, v252, 28
	v_readlane_b32 s5, v252, 17
	s_waitcnt vmcnt(10)
	v_cndmask_b32_e32 v7, v243, v247, vcc
	v_cmp_lt_i32_e32 vcc, v248, v245
	s_waitcnt vmcnt(8)
	v_lshlrev_b32_e32 v95, 2, v7
	v_readlane_b32 s17, v252, 29
	v_cndmask_b32_e32 v7, v243, v248, vcc
	v_cmp_lt_i32_e32 vcc, v249, v245
	s_add_u32 s4, s16, s0
	v_and_b32_e32 v3, 63, v4
	v_lshlrev_b32_e32 v96, 2, v7
	v_cndmask_b32_e32 v7, v243, v249, vcc
	s_addc_u32 s5, s17, s1
	v_lshlrev_b32_e32 v6, 4, v3
	v_lshlrev_b32_e32 v97, 2, v7
	v_mov_b32_e32 v7, v1
	v_readlane_b32 s6, v252, 18
	v_readlane_b32 s7, v252, 19
	v_readlane_b32 s8, v252, 20
	v_readlane_b32 s9, v252, 21
	v_readlane_b32 s10, v252, 22
	v_readlane_b32 s11, v252, 23
	v_readlane_b32 s12, v252, 24
	v_readlane_b32 s13, v252, 25
	v_readlane_b32 s14, v252, 26
	v_readlane_b32 s15, v252, 27
	v_readlane_b32 s18, v252, 30
	v_readlane_b32 s19, v252, 31
	v_lshlrev_b32_e32 v93, 2, v0
	v_and_b32_e32 v0, 1, v4
	v_bfe_u32 v5, v4, 1, 4
	v_lshl_add_u64 v[36:37], s[4:5], 0, v[6:7]
	v_and_b32_e32 v7, 8, v4
	v_readlane_b32 s60, v252, 32
	v_lshlrev_b32_e32 v34, 2, v3
	v_cmp_eq_u32_e64 s[0:1], 0, v0
	v_lshl_or_b32 v0, s96, 4, v5
	v_bfe_u32 v94, v4, 5, 1
	v_cmp_eq_u32_e64 s[36:37], 0, v7
	v_and_b32_e32 v7, 4, v4
	v_and_b32_e32 v4, 2, v4
	v_readlane_b32 s4, v254, 45
	v_readlane_b32 s66, v252, 38
	v_readlane_b32 s67, v252, 39
	v_add_u32_e32 v92, 0, v6
	v_or_b32_e32 v6, 0x100, v34
	v_or_b32_e32 v8, 0x200, v34
	v_or_b32_e32 v10, 0x300, v34
	v_cmp_eq_u32_e64 s[42:43], 0, v4
	v_lshlrev_b32_e32 v4, 2, v5
	v_mov_b32_e32 v5, v1
	v_readlane_b32 s5, v254, 46
	v_readlane_b32 s14, v254, 55
	v_readlane_b32 s15, v254, 56
	v_readlane_b32 s18, v254, 59
	v_readlane_b32 s19, v254, 60
	v_lshl_add_u64 v[40:41], v[0:1], 2, s[66:67]
	v_lshlrev_b32_e32 v0, 3, v3
	v_readlane_b32 s4, v254, 13
	v_cmp_eq_u32_e64 s[40:41], 0, v7
	v_lshl_add_u64 v[38:39], s[14:15], 0, v[4:5]
	v_lshl_add_u64 v[42:43], s[18:19], 0, v[0:1]
	v_lshl_add_u32 v44, v2, 1, s4
	s_mov_b64 s[4:5], 0
	v_lshlrev_b32_e32 v46, 2, v6
	v_lshlrev_b32_e32 v48, 2, v8
	v_lshlrev_b32_e32 v50, 2, v10
	v_readlane_b32 s6, v254, 47
	v_readlane_b32 s7, v254, 48
	v_readlane_b32 s8, v254, 49
	v_readlane_b32 s9, v254, 50
	v_readlane_b32 s10, v254, 51
	v_readlane_b32 s11, v254, 52
	v_readlane_b32 s12, v254, 53
	v_readlane_b32 s13, v254, 54
	v_readlane_b32 s16, v254, 57
	v_readlane_b32 s17, v254, 58
	v_readlane_b32 s61, v252, 33
	v_readlane_b32 s62, v252, 34
	v_readlane_b32 s63, v252, 35
	v_readlane_b32 s64, v252, 36
	v_readlane_b32 s65, v252, 37
	v_readlane_b32 s68, v252, 40
	v_readlane_b32 s69, v252, 41
	v_readlane_b32 s70, v252, 42
	v_readlane_b32 s71, v252, 43
	v_readlane_b32 s72, v252, 44
	v_readlane_b32 s73, v252, 45
	v_readlane_b32 s74, v252, 46
	v_readlane_b32 s75, v252, 47
	v_readlane_b32 s98, v252, 16
	v_readlane_b32 s99, v252, 17
	v_readlane_b32 s100, v252, 8
	v_readlane_b32 s101, v252, 9
	s_nop 3
	s_cmp_lg_u64 s[24:25], 0
	s_cselect_b32 s98, s100, s98
	s_cselect_b32 s99, s101, s99
	v_mov_b32_e32 v218, s98
	v_mov_b32_e32 v219, s99
	v_readlane_b32 s98, v252, 20
	v_readlane_b32 s99, v252, 21
	v_readlane_b32 s100, v254, 57
	v_readlane_b32 s101, v254, 58
	s_nop 3
	s_cselect_b32 s98, s100, s98
	s_cselect_b32 s99, s101, s99
	v_mov_b32_e32 v220, s98
	v_mov_b32_e32 v221, s99
	s_mov_b32 s101, 0
	s_branch .LBB0_75

; __device__ void norm_phase(const Params& p, int layer, int which, int nrows, char* smem) {
;     ...
; #pragma unroll
;     for (int i = 0; i < 4; ++i) {
;       v[0][i] = *(const f32x4*)(src + i * 256 + lane * 4);
;       v[1][i] = *(const f32x4*)(src + DM + i * 256 + lane * 4);
;     }
;     if (which == 0 && layer == 1 && !latent) {
;       const float* pb = (const float*)p.obuf + (size_t)(row0 - NLAT) * DM;
; #pragma unroll
;       for (int q = 0; q < 4; ++q)
; #pragma unroll
;         for (int i = 0; i < 4; ++i) {
;           v[0][i] += *(const f32x4*)(pb + (size_t)q * (NBATCH * CTXL) * DM + i * 256 + lane * 4);
;           v[1][i] += *(const f32x4*)(pb + (size_t)q * (NBATCH * CTXL) * DM + DM + i * 256 + lane * 4);
;         }
;     }
.LBB0_87:
	v_lshlrev_b64 v[4:5], 12, v[4:5]
	s_waitcnt lgkmcnt(0)
	v_lshl_add_u64 v[2:3], v[2:3], 0, v[4:5]
	v_lshlrev_b32_e32 v0, 2, v34
	v_lshl_add_u64 v[2:3], v[2:3], 0, v[0:1]
	v_add_co_u32_e32 v26, vcc, 0x1000, v2
	v_lshl_add_u64 v[30:31], v[2:3], 0, s[26:27]
	s_nop 0
	v_addc_co_u32_e32 v27, vcc, 0, v3, vcc
	s_cmp_lg_u32 s101, 0
	s_cbranch_scc1 .Lnorm_copy
	global_load_dwordx4 v[22:25], v[2:3], off
	global_load_dwordx4 v[14:17], v[2:3], off offset:1024
	global_load_dwordx4 v[18:21], v[30:31], off offset:1024
	global_load_dwordx4 v[6:9], v[30:31], off offset:2048
	global_load_dwordx4 v[10:13], v[2:3], off offset:2048
	s_nop 0
	global_load_dwordx4 v[2:5], v[2:3], off offset:3072
	s_nop 0
	global_load_dwordx4 v[26:29], v[26:27], off
	s_nop 0
	global_load_dwordx4 v[30:33], v[30:31], off offset:3072
	s_branch .Lnorm_cont
.Lnorm_copy:
	s_waitcnt vmcnt(0)
	v_mov_b64_e32 v[22:23], v[134:135]
	v_mov_b64_e32 v[24:25], v[136:137]
	v_mov_b64_e32 v[14:15], v[138:139]
	v_mov_b64_e32 v[16:17], v[140:141]
	v_mov_b64_e32 v[10:11], v[142:143]
	v_mov_b64_e32 v[12:13], v[144:145]
	v_mov_b64_e32 v[2:3], v[146:147]
	v_mov_b64_e32 v[4:5], v[148:149]
	v_mov_b64_e32 v[26:27], v[150:151]
	v_mov_b64_e32 v[28:29], v[152:153]
	v_mov_b64_e32 v[18:19], v[154:155]
	v_mov_b64_e32 v[20:21], v[156:157]
	v_mov_b64_e32 v[6:7], v[158:159]
	v_mov_b64_e32 v[8:9], v[160:161]
	v_mov_b64_e32 v[30:31], v[162:163]
	v_mov_b64_e32 v[32:33], v[164:165]
.Lnorm_cont:
	v_readlane_b32 s6, v254, 32
	v_readlane_b32 s7, v254, 33
	s_nor_b64 s[8:9], s[6:7], s[44:45]
	s_and_saveexec_b64 s[6:7], s[8:9]
	s_cbranch_execz .LBB0_89
	v_add_u32_e32 v52, 0xffff8000, v44
	v_mov_b32_e32 v53, v1
	v_lshlrev_b64 v[52:53], 12, v[52:53]
	v_lshl_add_u64 v[52:53], s[82:83], 0, v[52:53]
	v_lshl_add_u64 v[52:53], v[52:53], 0, v[0:1]
	s_mov_b64 s[8:9], 0x1000
	v_lshl_add_u64 v[134:135], v[52:53], 0, s[8:9]
	s_mov_b64 s[8:9], 0x1000000
	v_lshl_add_u64 v[136:137], v[52:53], 0, s[8:9]
	v_lshl_add_u64 v[138:139], v[134:135], 0, s[8:9]
	v_lshl_add_u64 v[140:141], v[136:137], 0, s[8:9]
	v_lshl_add_u64 v[142:143], v[138:139], 0, s[8:9]
	v_lshl_add_u64 v[144:145], v[140:141], 0, s[8:9]
	v_lshl_add_u64 v[146:147], v[142:143], 0, s[8:9]
	global_load_dwordx4 v[148:151], v[52:53], off
	global_load_dwordx4 v[152:155], v[52:53], off offset:1024
	global_load_dwordx4 v[156:159], v[52:53], off offset:2048
	global_load_dwordx4 v[160:163], v[52:53], off offset:3072
	global_load_dwordx4 v[164:167], v[134:135], off
	global_load_dwordx4 v[168:171], v[134:135], off offset:1024
	global_load_dwordx4 v[178:181], v[134:135], off offset:2048
	global_load_dwordx4 v[182:185], v[134:135], off offset:3072
	global_load_dwordx4 v[186:189], v[136:137], off
	global_load_dwordx4 v[190:193], v[136:137], off offset:1024
	global_load_dwordx4 v[194:197], v[136:137], off offset:2048
	global_load_dwordx4 v[198:201], v[136:137], off offset:3072
	global_load_dwordx4 v[202:205], v[138:139], off
	global_load_dwordx4 v[206:209], v[138:139], off offset:1024
	global_load_dwordx4 v[210:213], v[138:139], off offset:2048
	global_load_dwordx4 v[214:217], v[138:139], off offset:3072
	s_waitcnt vmcnt(8)
	v_pk_add_f32 v[22:23], v[22:23], v[148:149]
	v_pk_add_f32 v[24:25], v[24:25], v[150:151]
	v_pk_add_f32 v[14:15], v[14:15], v[152:153]
	v_pk_add_f32 v[16:17], v[16:17], v[154:155]
	v_pk_add_f32 v[10:11], v[10:11], v[156:157]
	v_pk_add_f32 v[12:13], v[12:13], v[158:159]
	v_pk_add_f32 v[2:3], v[2:3], v[160:161]
	v_pk_add_f32 v[4:5], v[4:5], v[162:163]
	v_pk_add_f32 v[26:27], v[26:27], v[164:165]
	v_pk_add_f32 v[28:29], v[28:29], v[166:167]
	v_pk_add_f32 v[18:19], v[18:19], v[168:169]
	v_pk_add_f32 v[20:21], v[20:21], v[170:171]
	v_pk_add_f32 v[6:7], v[6:7], v[178:179]
	v_pk_add_f32 v[8:9], v[8:9], v[180:181]
	v_pk_add_f32 v[30:31], v[30:31], v[182:183]
	v_pk_add_f32 v[32:33], v[32:33], v[184:185]
	global_load_dwordx4 v[148:151], v[140:141], off
	global_load_dwordx4 v[152:155], v[140:141], off offset:1024
	global_load_dwordx4 v[156:159], v[140:141], off offset:2048
	global_load_dwordx4 v[160:163], v[140:141], off offset:3072
	global_load_dwordx4 v[164:167], v[142:143], off
	global_load_dwordx4 v[168:171], v[142:143], off offset:1024
	global_load_dwordx4 v[178:181], v[142:143], off offset:2048
	global_load_dwordx4 v[182:185], v[142:143], off offset:3072
	s_waitcnt vmcnt(8)
	v_pk_add_f32 v[22:23], v[22:23], v[186:187]
	v_pk_add_f32 v[24:25], v[24:25], v[188:189]
	v_pk_add_f32 v[14:15], v[14:15], v[190:191]
	v_pk_add_f32 v[16:17], v[16:17], v[192:193]
	v_pk_add_f32 v[10:11], v[10:11], v[194:195]
	v_pk_add_f32 v[12:13], v[12:13], v[196:197]
	v_pk_add_f32 v[2:3], v[2:3], v[198:199]
	v_pk_add_f32 v[4:5], v[4:5], v[200:201]
	v_pk_add_f32 v[26:27], v[26:27], v[202:203]
	v_pk_add_f32 v[28:29], v[28:29], v[204:205]
	v_pk_add_f32 v[18:19], v[18:19], v[206:207]
	v_pk_add_f32 v[20:21], v[20:21], v[208:209]
	v_pk_add_f32 v[6:7], v[6:7], v[210:211]
	v_pk_add_f32 v[8:9], v[8:9], v[212:213]
	v_pk_add_f32 v[30:31], v[30:31], v[214:215]
	v_pk_add_f32 v[32:33], v[32:33], v[216:217]
	global_load_dwordx4 v[186:189], v[144:145], off
	global_load_dwordx4 v[190:193], v[144:145], off offset:1024
	global_load_dwordx4 v[194:197], v[144:145], off offset:2048
	global_load_dwordx4 v[198:201], v[144:145], off offset:3072
	global_load_dwordx4 v[202:205], v[146:147], off
	global_load_dwordx4 v[206:209], v[146:147], off offset:1024
	global_load_dwordx4 v[210:213], v[146:147], off offset:2048
	global_load_dwordx4 v[214:217], v[146:147], off offset:3072
	s_waitcnt vmcnt(8)
	v_pk_add_f32 v[22:23], v[22:23], v[148:149]
	v_pk_add_f32 v[24:25], v[24:25], v[150:151]
	v_pk_add_f32 v[14:15], v[14:15], v[152:153]
	v_pk_add_f32 v[16:17], v[16:17], v[154:155]
	v_pk_add_f32 v[10:11], v[10:11], v[156:157]
	v_pk_add_f32 v[12:13], v[12:13], v[158:159]
	v_pk_add_f32 v[2:3], v[2:3], v[160:161]
	v_pk_add_f32 v[4:5], v[4:5], v[162:163]
	v_pk_add_f32 v[26:27], v[26:27], v[164:165]
	v_pk_add_f32 v[28:29], v[28:29], v[166:167]
	v_pk_add_f32 v[18:19], v[18:19], v[168:169]
	v_pk_add_f32 v[20:21], v[20:21], v[170:171]
	v_pk_add_f32 v[6:7], v[6:7], v[178:179]
	v_pk_add_f32 v[8:9], v[8:9], v[180:181]
	v_pk_add_f32 v[30:31], v[30:31], v[182:183]
	v_pk_add_f32 v[32:33], v[32:33], v[184:185]
	s_waitcnt vmcnt(0)
	v_pk_add_f32 v[22:23], v[22:23], v[186:187]
	v_pk_add_f32 v[24:25], v[24:25], v[188:189]
	v_pk_add_f32 v[14:15], v[14:15], v[190:191]
	v_pk_add_f32 v[16:17], v[16:17], v[192:193]
	v_pk_add_f32 v[10:11], v[10:11], v[194:195]
	v_pk_add_f32 v[12:13], v[12:13], v[196:197]
	v_pk_add_f32 v[2:3], v[2:3], v[198:199]
	v_pk_add_f32 v[4:5], v[4:5], v[200:201]
	v_pk_add_f32 v[26:27], v[26:27], v[202:203]
	v_pk_add_f32 v[28:29], v[28:29], v[204:205]
	v_pk_add_f32 v[18:19], v[18:19], v[206:207]
	v_pk_add_f32 v[20:21], v[20:21], v[208:209]
	v_pk_add_f32 v[6:7], v[6:7], v[210:211]
	v_pk_add_f32 v[8:9], v[8:9], v[212:213]
	v_pk_add_f32 v[30:31], v[30:31], v[214:215]
	v_pk_add_f32 v[32:33], v[32:33], v[216:217]
; DI float xsum32(float x) { auto r = __builtin_amdgcn_permlane32_swap(__float_as_uint(x), __float_as_uint(x), false, false); return __uint_as_float(r[0]) + __uint_as_float(r[1]); }
; DI float xsum16(float x) { auto r = __builtin_amdgcn_permlane16_swap(__float_as_uint(x), __float_as_uint(x), false, false); return __uint_as_float(r[0]) + __uint_as_float(r[1]); }
; __device__ void norm_phase(const Params& p, int layer, int which, int nrows, char* smem) {
;     ...
; #pragma unroll
;     for (int i = 0; i < 4; ++i) {
;       ss0 += v[0][i][0] * v[0][i][0] + v[0][i][1] * v[0][i][1] + v[0][i][2] * v[0][i][2] + v[0][i][3] * v[0][i][3];
;       ss1 += v[1][i][0] * v[1][i][0] + v[1][i][1] * v[1][i][1] + v[1][i][2] * v[1][i][2] + v[1][i][3] * v[1][i][3];
;     }
;     ss0 = xsum16(xsum32(ss0)); ss1 = xsum16(xsum32(ss1));
; #pragma unroll
;     for (int o = 8; o > 0; o >>= 1) { ss0 += __shfl_xor(ss0, o); ss1 += __shfl_xor(ss1, o); }
;     const float rs0 = __builtin_amdgcn_rsqf(ss0 * (1.f / DM) + EPSN), rs1 = __builtin_amdgcn_rsqf(ss1 * (1.f / DM) + EPSN);
; #pragma unroll
;     for (int i = 0; i < 4; ++i) {
;       const int c0 = i * 256 + lane * 4;
;       const f32x4 gv = *(const f32x4*)(g + c0), sh = *(const f32x4*)(shift + c0), sc = *(const f32x4*)(scale + c0) + 1.f;
;       v[0][i] = (v[0][i] * rs0 * gv) * sc + sh;
;       v[1][i] = (v[1][i] * rs1 * gv) * sc + sh;
;       u32x2 o;
;       o[0] = pk_bf16(v[0][i][0], v[0][i][1]);
;       o[1] = pk_bf16(v[0][i][2], v[0][i][3]);
;       *(u32x2*)(p.xn + (size_t)row0 * DM + c0) = o;
;       o[0] = pk_bf16(v[1][i][0], v[1][i][1]);
;       o[1] = pk_bf16(v[1][i][2], v[1][i][3]);
;       *(u32x2*)(p.xn + (size_t)(row0 + 1) * DM + c0) = o;
.LBB0_89:
	s_or_b64 exec, exec, s[6:7]
	v_min_i32_e32 v45, 0x4000, v35
	v_ashrrev_i32_e32 v45, 10, v45
	v_add_u32_e32 v45, s56, v45
	v_mul_i32_i24_e32 v52, 6, v45
	v_ashrrev_i32_e32 v53, 31, v52
	v_readlane_b32 s8, v254, 45
	v_lshlrev_b64 v[52:53], 12, v[52:53]
	v_readlane_b32 s12, v254, 49
	v_readlane_b32 s13, v254, 50
	s_waitcnt vmcnt(1)
	v_mul_f32_e32 v47, v27, v27
	v_fmac_f32_e32 v47, v26, v26
	v_lshl_add_u64 v[54:55], s[12:13], 0, v[52:53]
	v_lshl_add_u64 v[52:53], v[54:55], 0, s[26:27]
	v_lshl_add_u64 v[70:71], v[54:55], 0, v[0:1]
	v_lshl_add_u64 v[58:59], v[52:53], 0, v[0:1]
	global_load_dwordx4 v[54:57], v[70:71], off
	s_nop 0
	global_load_dwordx4 v[58:61], v[58:59], off
	v_mul_f32_e32 v0, v19, v19
	global_load_dwordx4 v[62:65], v[36:37], off
	v_fmac_f32_e32 v0, v18, v18
	v_fmac_f32_e32 v47, v28, v28
	v_fmac_f32_e32 v0, v20, v20
	v_mul_f32_e32 v45, v23, v23
	v_fmac_f32_e32 v47, v29, v29
	v_mul_f32_e32 v49, v15, v15
	v_fmac_f32_e32 v0, v21, v21
	v_fmac_f32_e32 v45, v22, v22
	v_fmac_f32_e32 v49, v14, v14
	v_add_f32_e32 v0, v47, v0
	v_mul_f32_e32 v47, v11, v11
	v_fmac_f32_e32 v45, v24, v24
	v_fmac_f32_e32 v49, v16, v16
	v_fmac_f32_e32 v47, v10, v10
	v_fmac_f32_e32 v45, v25, v25
	v_fmac_f32_e32 v49, v17, v17
	v_fmac_f32_e32 v47, v12, v12
	v_add_f32_e32 v45, v45, v49
	v_fmac_f32_e32 v47, v13, v13
	v_add_f32_e32 v45, v45, v47
	v_mul_f32_e32 v47, v7, v7
	v_fmac_f32_e32 v47, v6, v6
	v_fmac_f32_e32 v47, v8, v8
	v_fmac_f32_e32 v47, v9, v9
	v_add_f32_e32 v0, v0, v47
	v_mul_f32_e32 v47, v3, v3
	v_fmac_f32_e32 v47, v2, v2
	v_fmac_f32_e32 v47, v4, v4
	v_fmac_f32_e32 v47, v5, v5
	v_add_f32_e32 v45, v45, v47
	s_waitcnt vmcnt(3)
	v_mul_f32_e32 v47, v31, v31
	v_fmac_f32_e32 v47, v30, v30
	v_fmac_f32_e32 v47, v32, v32
	v_fmac_f32_e32 v47, v33, v33
	v_add_f32_e32 v0, v0, v47
	v_mov_b32_e32 v47, v45
	s_nop 1
	v_permlane32_swap_b32_e32 v45, v47
	v_add_f32_e32 v45, v45, v47
	v_mov_b32_e32 v47, v45
	s_nop 1
	v_permlane16_swap_b32_e32 v45, v47
	v_add_f32_e32 v45, v45, v47
	v_mov_b32_e32 v47, v0
	s_nop 1
	v_permlane32_swap_b32_e32 v0, v47
	v_add_f32_e32 v0, v0, v47
	v_mov_b32_e32 v47, v0
	s_nop 1
	v_permlane16_swap_b32_e32 v0, v47
	v_add_f32_e32 v0, v0, v47
	ds_bpermute_b32 v47, v95, v45
	ds_bpermute_b32 v49, v95, v0
	v_add_u32_e32 v68, 1, v44
	v_ashrrev_i32_e32 v69, 31, v68
	v_lshlrev_b64 v[68:69], 11, v[68:69]
	s_waitcnt lgkmcnt(1)
	v_add_f32_e32 v45, v45, v47
	s_waitcnt lgkmcnt(0)
	v_add_f32_e32 v0, v0, v49
	ds_bpermute_b32 v47, v96, v45
	ds_bpermute_b32 v49, v96, v0
	v_mov_b32_e32 v51, v1
	v_readlane_b32 s9, v254, 46
	v_readlane_b32 s10, v254, 47
	s_waitcnt lgkmcnt(1)
	v_add_f32_e32 v45, v45, v47
	s_waitcnt lgkmcnt(0)
	v_add_f32_e32 v0, v0, v49
	ds_bpermute_b32 v47, v97, v45
	ds_bpermute_b32 v49, v97, v0
	v_readlane_b32 s11, v254, 48
	v_readlane_b32 s14, v254, 51
	v_readlane_b32 s15, v254, 52
	s_waitcnt lgkmcnt(1)
	v_add_f32_e32 v45, v45, v47
	s_waitcnt lgkmcnt(0)
	v_add_f32_e32 v0, v0, v49
	ds_bpermute_b32 v47, v93, v45
	ds_bpermute_b32 v49, v93, v0
	v_readlane_b32 s16, v254, 53
	v_readlane_b32 s17, v254, 54
	v_readlane_b32 s18, v254, 55
	s_waitcnt lgkmcnt(1)
	v_add_f32_e32 v45, v45, v47
	s_waitcnt lgkmcnt(0)
	v_add_f32_e32 v47, v0, v49
	v_fmamk_f32 v0, v45, 0x3a800000, v236
	v_rsq_f32_e32 v0, v0
	v_fmamk_f32 v45, v47, 0x3a800000, v236
	v_rsq_f32_e32 v90, v45
	v_ashrrev_i32_e32 v45, 31, v44
	v_pk_mul_f32 v[24:25], v[24:25], v[0:1] op_sel_hi:[1,0]
	v_pk_mul_f32 v[22:23], v[22:23], v[0:1] op_sel_hi:[1,0]
	s_waitcnt vmcnt(1)
	v_pk_add_f32 v[60:61], v[60:61], 1.0 op_sel_hi:[1,0]
	v_pk_add_f32 v[58:59], v[58:59], 1.0 op_sel_hi:[1,0]
	s_waitcnt vmcnt(0)
	v_pk_mul_f32 v[72:73], v[62:63], v[22:23]
	v_pk_mul_f32 v[22:23], v[64:65], v[24:25]
	v_pk_mul_f32 v[28:29], v[28:29], v[90:91] op_sel_hi:[1,0]
	v_pk_mul_f32 v[26:27], v[26:27], v[90:91] op_sel_hi:[1,0]
	v_lshlrev_b64 v[66:67], 11, v[44:45]
	v_pk_fma_f32 v[22:23], v[60:61], v[22:23], v[56:57]
	v_pk_fma_f32 v[24:25], v[58:59], v[72:73], v[54:55]
	v_pk_mul_f32 v[62:63], v[62:63], v[26:27]
	v_pk_mul_f32 v[26:27], v[64:65], v[28:29]
	v_pk_fma_f32 v[28:29], v[58:59], v[62:63], v[54:55]
	v_pk_fma_f32 v[26:27], v[60:61], v[26:27], v[56:57]
	v_cvt_pk_bf16_f32 v56, v24, v25
	v_cvt_pk_bf16_f32 v57, v22, v23
	v_lshl_add_u64 v[54:55], v[42:43], 0, v[66:67]
	global_store_dwordx2 v[54:55], v[56:57], off
	v_cvt_pk_bf16_f32 v58, v28, v29
	v_cvt_pk_bf16_f32 v59, v26, v27
	v_lshl_add_u64 v[56:57], v[42:43], 0, v[68:69]
	v_mov_b32_e32 v47, v1
	global_store_dwordx2 v[56:57], v[58:59], off
	v_lshl_add_u64 v[58:59], v[52:53], 0, v[46:47]
	global_load_dwordx4 v[58:61], v[58:59], off
	s_nop 0
	global_load_dwordx4 v[62:65], v[36:37], off offset:1024
	global_load_dwordx4 v[66:69], v[70:71], off offset:1024
	v_pk_mul_f32 v[16:17], v[16:17], v[0:1] op_sel_hi:[1,0]
	v_pk_mul_f32 v[14:15], v[14:15], v[0:1] op_sel_hi:[1,0]
	v_pk_mul_f32 v[20:21], v[20:21], v[90:91] op_sel_hi:[1,0]
	v_pk_mul_f32 v[18:19], v[18:19], v[90:91] op_sel_hi:[1,0]
	v_mov_b32_e32 v49, v1
	v_lshl_add_u64 v[72:73], v[52:53], 0, v[48:49]
	v_pk_mul_f32 v[12:13], v[12:13], v[0:1] op_sel_hi:[1,0]
	v_pk_mul_f32 v[10:11], v[10:11], v[0:1] op_sel_hi:[1,0]
	v_pk_mul_f32 v[8:9], v[8:9], v[90:91] op_sel_hi:[1,0]
	v_pk_mul_f32 v[6:7], v[6:7], v[90:91] op_sel_hi:[1,0]
	v_lshl_add_u64 v[52:53], v[52:53], 0, v[50:51]
	v_pk_mul_f32 v[32:33], v[32:33], v[90:91] op_sel_hi:[1,0]
	v_pk_mul_f32 v[30:31], v[30:31], v[90:91] op_sel_hi:[1,0]
	v_pk_mul_f32 v[4:5], v[4:5], v[0:1] op_sel_hi:[1,0]
	v_pk_mul_f32 v[2:3], v[2:3], v[0:1] op_sel_hi:[1,0]
	v_readlane_b32 s19, v254, 56
	v_readlane_b32 s20, v254, 57
	v_readlane_b32 s21, v254, 58
	v_readlane_b32 s22, v254, 59
	v_readlane_b32 s23, v254, 60
	s_waitcnt vmcnt(2)
; __device__ void norm_phase(const Params& p, int layer, int which, int nrows, char* smem) {
;     ...
;       const f32x4 gv = *(const f32x4*)(g + c0), sh = *(const f32x4*)(shift + c0), sc = *(const f32x4*)(scale + c0) + 1.f;
;       v[0][i] = (v[0][i] * rs0 * gv) * sc + sh;
;       v[1][i] = (v[1][i] * rs1 * gv) * sc + sh;
;       u32x2 o;
;       o[0] = pk_bf16(v[0][i][0], v[0][i][1]);
;       o[1] = pk_bf16(v[0][i][2], v[0][i][3]);
;       *(u32x2*)(p.xn + (size_t)row0 * DM + c0) = o;
;       o[0] = pk_bf16(v[1][i][0], v[1][i][1]);
;       o[1] = pk_bf16(v[1][i][2], v[1][i][3]);
;       *(u32x2*)(p.xn + (size_t)(row0 + 1) * DM + c0) = o;
;     }
;     if (which == 0) {
;       float a32[32];
;       typedef float f32x2 __attribute__((ext_vector_type(2)));
; #pragma unroll
;       for (int n = 0; n < 16; ++n) {
;         f32x2 a0 = {0.f, 0.f}, a1 = {0.f, 0.f};
; #pragma unroll
;         for (int i = 0; i < 4; ++i) {
;           const f32x4 wv = *(const f32x4*)(wgs + n * DM + i * 256 + lane * 4);
;           const f32x2 wlo = {wv[0], wv[1]}, whi = {wv[2], wv[3]};
;           a0 += (f32x2){v[0][i][0], v[0][i][1]} * wlo;
;           a0 += (f32x2){v[0][i][2], v[0][i][3]} * whi;
;           a1 += (f32x2){v[1][i][0], v[1][i][1]} * wlo;
;           a1 += (f32x2){v[1][i][2], v[1][i][3]} * whi;
;         }
;         a32[n] = a0[0] + a0[1];
;         a32[16 + n] = a1[0] + a1[1];
	v_pk_add_f32 v[60:61], v[60:61], 1.0 op_sel_hi:[1,0]
	v_pk_add_f32 v[58:59], v[58:59], 1.0 op_sel_hi:[1,0]
	s_waitcnt vmcnt(1)
	v_pk_mul_f32 v[74:75], v[62:63], v[14:15]
	v_pk_mul_f32 v[14:15], v[64:65], v[16:17]
	v_pk_mul_f32 v[18:19], v[62:63], v[18:19]
	v_pk_mul_f32 v[16:17], v[64:65], v[20:21]
	s_waitcnt vmcnt(0)
	v_pk_fma_f32 v[14:15], v[14:15], v[60:61], v[68:69]
	v_pk_fma_f32 v[20:21], v[74:75], v[58:59], v[66:67]
	v_pk_fma_f32 v[16:17], v[60:61], v[16:17], v[68:69]
	v_pk_fma_f32 v[18:19], v[58:59], v[18:19], v[66:67]
	v_cvt_pk_bf16_f32 v58, v20, v21
	v_cvt_pk_bf16_f32 v59, v14, v15
	v_cvt_pk_bf16_f32 v60, v18, v19
	v_cvt_pk_bf16_f32 v61, v16, v17
	global_store_dwordx2 v[54:55], v[58:59], off offset:512
	global_store_dwordx2 v[56:57], v[60:61], off offset:512
	global_load_dwordx4 v[58:61], v[72:73], off
	s_nop 0
	global_load_dwordx4 v[62:65], v[36:37], off offset:2048
	global_load_dwordx4 v[66:69], v[70:71], off offset:2048
	s_waitcnt vmcnt(2)
	v_pk_add_f32 v[60:61], v[60:61], 1.0 op_sel_hi:[1,0]
	v_pk_add_f32 v[58:59], v[58:59], 1.0 op_sel_hi:[1,0]
	s_waitcnt vmcnt(1)
	v_pk_mul_f32 v[10:11], v[10:11], v[62:63]
	v_pk_mul_f32 v[12:13], v[12:13], v[64:65]
	v_pk_mul_f32 v[62:63], v[6:7], v[62:63]
	v_pk_mul_f32 v[8:9], v[8:9], v[64:65]
	s_waitcnt vmcnt(0)
	v_pk_fma_f32 v[6:7], v[12:13], v[60:61], v[68:69]
	v_pk_fma_f32 v[12:13], v[10:11], v[58:59], v[66:67]
	v_pk_fma_f32 v[8:9], v[8:9], v[60:61], v[68:69]
	v_pk_fma_f32 v[10:11], v[62:63], v[58:59], v[66:67]
	v_cvt_pk_bf16_f32 v58, v12, v13
	v_cvt_pk_bf16_f32 v59, v6, v7
	v_cvt_pk_bf16_f32 v60, v10, v11
	v_cvt_pk_bf16_f32 v61, v8, v9
	global_store_dwordx2 v[54:55], v[58:59], off offset:1024
	global_store_dwordx2 v[56:57], v[60:61], off offset:1024
	global_load_dwordx4 v[58:61], v[52:53], off
	s_nop 0
	global_load_dwordx4 v[62:65], v[36:37], off offset:3072
	global_load_dwordx4 v[66:69], v[70:71], off offset:3072
	ds_read_b128 v[70:73], v92
	ds_read_b128 v[74:77], v92 offset:1024
	ds_read_b128 v[78:81], v92 offset:2048
	ds_read_b128 v[82:85], v92 offset:3072
	ds_read_b128 v[86:89], v92 offset:7168
	ds_read_b128 v[98:101], v92 offset:6144
	ds_read_b128 v[102:105], v92 offset:5120
	ds_read_b128 v[106:109], v92 offset:4096
	s_waitcnt lgkmcnt(7)
	v_pk_fma_f32 v[52:53], v[24:25], v[70:71], 0 op_sel_hi:[1,1,0]
	v_pk_fma_f32 v[70:71], v[28:29], v[70:71], 0 op_sel_hi:[1,1,0]
	v_pk_fma_f32 v[52:53], v[22:23], v[72:73], v[52:53]
	v_pk_fma_f32 v[70:71], v[26:27], v[72:73], v[70:71]
	s_waitcnt lgkmcnt(0)
	v_pk_fma_f32 v[90:91], v[24:25], v[106:107], 0 op_sel_hi:[1,1,0]
	v_pk_fma_f32 v[106:107], v[28:29], v[106:107], 0 op_sel_hi:[1,1,0]
	v_pk_fma_f32 v[72:73], v[22:23], v[108:109], v[90:91]
	v_pk_fma_f32 v[90:91], v[26:27], v[108:109], v[106:107]
	v_pk_fma_f32 v[52:53], v[20:21], v[74:75], v[52:53]
	v_pk_fma_f32 v[70:71], v[18:19], v[74:75], v[70:71]
	v_pk_fma_f32 v[72:73], v[20:21], v[102:103], v[72:73]
	v_pk_fma_f32 v[74:75], v[18:19], v[102:103], v[90:91]
	v_pk_fma_f32 v[52:53], v[14:15], v[76:77], v[52:53]
	v_pk_fma_f32 v[70:71], v[16:17], v[76:77], v[70:71]
	v_pk_fma_f32 v[72:73], v[14:15], v[104:105], v[72:73]
	v_pk_fma_f32 v[74:75], v[16:17], v[104:105], v[74:75]
	v_pk_fma_f32 v[52:53], v[12:13], v[78:79], v[52:53]
	v_pk_fma_f32 v[70:71], v[10:11], v[78:79], v[70:71]
	v_pk_fma_f32 v[72:73], v[12:13], v[98:99], v[72:73]
	v_pk_fma_f32 v[74:75], v[10:11], v[98:99], v[74:75]
	v_pk_fma_f32 v[52:53], v[6:7], v[80:81], v[52:53]
	v_pk_fma_f32 v[70:71], v[8:9], v[80:81], v[70:71]
	v_pk_fma_f32 v[72:73], v[6:7], v[100:101], v[72:73]
	v_pk_fma_f32 v[74:75], v[8:9], v[100:101], v[74:75]
	s_waitcnt vmcnt(2)
	v_pk_add_f32 v[60:61], v[60:61], 1.0 op_sel_hi:[1,0]
	v_pk_add_f32 v[58:59], v[58:59], 1.0 op_sel_hi:[1,0]
	s_waitcnt vmcnt(1)
	v_pk_mul_f32 v[76:77], v[2:3], v[62:63]
	v_pk_mul_f32 v[2:3], v[4:5], v[64:65]
	v_pk_mul_f32 v[30:31], v[30:31], v[62:63]
	v_pk_mul_f32 v[4:5], v[32:33], v[64:65]
	s_waitcnt vmcnt(0)
	v_pk_fma_f32 v[2:3], v[2:3], v[60:61], v[68:69]
	v_pk_fma_f32 v[32:33], v[76:77], v[58:59], v[66:67]
	v_pk_fma_f32 v[4:5], v[4:5], v[60:61], v[68:69]
	v_pk_fma_f32 v[30:31], v[30:31], v[58:59], v[66:67]
	v_cvt_pk_bf16_f32 v58, v32, v33
	v_cvt_pk_bf16_f32 v59, v2, v3
	v_cvt_pk_bf16_f32 v60, v30, v31
	v_cvt_pk_bf16_f32 v61, v4, v5
	v_pk_fma_f32 v[52:53], v[32:33], v[82:83], v[52:53]
	v_pk_fma_f32 v[62:63], v[30:31], v[82:83], v[70:71]
	v_pk_fma_f32 v[64:65], v[32:33], v[86:87], v[72:73]
	v_pk_fma_f32 v[66:67], v[30:31], v[86:87], v[74:75]
	global_store_dwordx2 v[54:55], v[58:59], off offset:1536
	global_store_dwordx2 v[56:57], v[60:61], off offset:1536
	v_readlane_b32 s100, v254, 14
	v_add_u32_e32 v180, s78, v35
	v_mov_b32_e32 v182, 0x47ff
	v_cmp_gt_i32_e64 s[98:99], v180, v182
	v_add_u32_e32 v181, s100, v44
	v_mov_b32_e32 v182, 0x4000
	v_cndmask_b32_e64 v180, v180, v35, s[98:99]
	v_cndmask_b32_e64 v181, v181, v44, s[98:99]
	v_cmp_lt_i32_e64 s[98:99], v180, v182
	v_add_u32_e32 v183, 0xffff8000, v181
	v_mov_b32_e32 v167, 0
	v_cndmask_b32_e64 v166, v183, v181, s[98:99]
	v_cndmask_b32_e64 v168, v220, v218, s[98:99]
	v_cndmask_b32_e64 v169, v221, v219, s[98:99]
	v_lshlrev_b64 v[166:167], 12, v[166:167]
	v_lshl_add_u64 v[168:169], v[168:169], 0, v[166:167]
	v_lshlrev_b32_e32 v166, 2, v34
	v_mov_b32_e32 v167, 0
	v_lshl_add_u64 v[168:169], v[168:169], 0, v[166:167]
	s_mov_b64 s[98:99], 0x1000
	v_lshl_add_u64 v[166:167], v[168:169], 0, s[98:99]
	global_load_dwordx4 v[134:137], v[168:169], off
	global_load_dwordx4 v[138:141], v[168:169], off offset:1024
	global_load_dwordx4 v[142:145], v[168:169], off offset:2048
	global_load_dwordx4 v[146:149], v[168:169], off offset:3072
	global_load_dwordx4 v[150:153], v[166:167], off
	global_load_dwordx4 v[154:157], v[166:167], off offset:1024
	global_load_dwordx4 v[158:161], v[166:167], off offset:2048
	global_load_dwordx4 v[162:165], v[166:167], off offset:3072
	s_mov_b32 s101, 1
	v_pk_fma_f32 v[52:53], v[2:3], v[84:85], v[52:53]
	v_pk_fma_f32 v[54:55], v[4:5], v[84:85], v[62:63]
	v_pk_fma_f32 v[60:61], v[2:3], v[88:89], v[64:65]
	v_pk_fma_f32 v[62:63], v[4:5], v[88:89], v[66:67]
	v_pk_add_f32 v[56:57], v[52:53], v[52:53] op_sel:[0,1] op_sel_hi:[1,0]
	v_pk_add_f32 v[58:59], v[54:55], v[54:55] op_sel:[0,1] op_sel_hi:[1,0]
	v_pk_add_f32 v[52:53], v[60:61], v[60:61] op_sel:[0,1] op_sel_hi:[1,0]
	v_pk_add_f32 v[54:55], v[62:63], v[62:63] op_sel:[0,1] op_sel_hi:[1,0]
	ds_read_b128 v[60:63], v92 offset:8192
	ds_read_b128 v[64:67], v92 offset:9216
	ds_read_b128 v[68:71], v92 offset:10240
	s_waitcnt lgkmcnt(2)
; __device__ void norm_phase(const Params& p, int layer, int which, int nrows, char* smem) {
;     ...
; #pragma unroll
;       for (int n = 0; n < 16; ++n) {
;         f32x2 a0 = {0.f, 0.f}, a1 = {0.f, 0.f};
; #pragma unroll
;         for (int i = 0; i < 4; ++i) {
;           const f32x4 wv = *(const f32x4*)(wgs + n * DM + i * 256 + lane * 4);
;           const f32x2 wlo = {wv[0], wv[1]}, whi = {wv[2], wv[3]};
;           a0 += (f32x2){v[0][i][0], v[0][i][1]} * wlo;
;           a0 += (f32x2){v[0][i][2], v[0][i][3]} * whi;
;           a1 += (f32x2){v[1][i][0], v[1][i][1]} * wlo;
;           a1 += (f32x2){v[1][i][2], v[1][i][3]} * whi;
;         }
;         a32[n] = a0[0] + a0[1];
;         a32[16 + n] = a1[0] + a1[1];
;         if ((n & 1) == 1) __builtin_amdgcn_sched_barrier(0);
;       }
	v_pk_fma_f32 v[72:73], v[24:25], v[60:61], 0 op_sel_hi:[1,1,0]
	v_pk_fma_f32 v[60:61], v[28:29], v[60:61], 0 op_sel_hi:[1,1,0]
	v_pk_fma_f32 v[72:73], v[22:23], v[62:63], v[72:73]
	v_pk_fma_f32 v[60:61], v[26:27], v[62:63], v[60:61]
	s_waitcnt lgkmcnt(1)
	v_pk_fma_f32 v[62:63], v[20:21], v[64:65], v[72:73]
	v_pk_fma_f32 v[60:61], v[18:19], v[64:65], v[60:61]
	v_pk_fma_f32 v[72:73], v[14:15], v[66:67], v[62:63]
	v_pk_fma_f32 v[64:65], v[16:17], v[66:67], v[60:61]
	ds_read_b128 v[60:63], v92 offset:11264
	s_waitcnt lgkmcnt(1)
	v_pk_fma_f32 v[66:67], v[12:13], v[68:69], v[72:73]
	v_pk_fma_f32 v[64:65], v[10:11], v[68:69], v[64:65]
	v_pk_fma_f32 v[66:67], v[6:7], v[70:71], v[66:67]
	v_pk_fma_f32 v[64:65], v[8:9], v[70:71], v[64:65]
	s_waitcnt lgkmcnt(0)
	v_pk_fma_f32 v[66:67], v[32:33], v[60:61], v[66:67]
	v_pk_fma_f32 v[60:61], v[30:31], v[60:61], v[64:65]
	v_pk_fma_f32 v[72:73], v[2:3], v[62:63], v[66:67]
	ds_read_b128 v[64:67], v92 offset:13312
	ds_read_b128 v[68:71], v92 offset:12288
	v_pk_fma_f32 v[62:63], v[4:5], v[62:63], v[60:61]
	v_pk_add_f32 v[60:61], v[72:73], v[72:73] op_sel:[0,1] op_sel_hi:[1,0]
	ds_read_b128 v[72:75], v92 offset:15360
	ds_read_b128 v[76:79], v92 offset:14336
	v_pk_add_f32 v[62:63], v[62:63], v[62:63] op_sel:[0,1] op_sel_hi:[1,0]
	s_waitcnt lgkmcnt(2)
	v_pk_fma_f32 v[80:81], v[24:25], v[68:69], 0 op_sel_hi:[1,1,0]
	v_pk_fma_f32 v[68:69], v[28:29], v[68:69], 0 op_sel_hi:[1,1,0]
	v_pk_fma_f32 v[80:81], v[22:23], v[70:71], v[80:81]
	v_pk_fma_f32 v[68:69], v[26:27], v[70:71], v[68:69]
	v_pk_fma_f32 v[70:71], v[20:21], v[64:65], v[80:81]
	v_pk_fma_f32 v[64:65], v[18:19], v[64:65], v[68:69]
	v_pk_fma_f32 v[70:71], v[14:15], v[66:67], v[70:71]
	v_pk_fma_f32 v[64:65], v[16:17], v[66:67], v[64:65]
	s_waitcnt lgkmcnt(0)
	v_pk_fma_f32 v[66:67], v[12:13], v[76:77], v[70:71]
	v_pk_fma_f32 v[64:65], v[10:11], v[76:77], v[64:65]
	v_pk_fma_f32 v[66:67], v[6:7], v[78:79], v[66:67]
	v_pk_fma_f32 v[64:65], v[8:9], v[78:79], v[64:65]
	v_pk_fma_f32 v[66:67], v[32:33], v[72:73], v[66:67]
	v_pk_fma_f32 v[64:65], v[30:31], v[72:73], v[64:65]
	v_pk_fma_f32 v[66:67], v[2:3], v[74:75], v[66:67]
	v_pk_fma_f32 v[68:69], v[4:5], v[74:75], v[64:65]
	v_pk_add_f32 v[64:65], v[66:67], v[66:67] op_sel:[0,1] op_sel_hi:[1,0]
	v_pk_add_f32 v[66:67], v[68:69], v[68:69] op_sel:[0,1] op_sel_hi:[1,0]
	ds_read_b128 v[68:71], v92 offset:16384
	ds_read_b128 v[72:75], v92 offset:17408
	ds_read_b128 v[76:79], v92 offset:18432
	s_waitcnt lgkmcnt(2)
	v_pk_fma_f32 v[80:81], v[24:25], v[68:69], 0 op_sel_hi:[1,1,0]
	v_pk_fma_f32 v[68:69], v[28:29], v[68:69], 0 op_sel_hi:[1,1,0]
	v_pk_fma_f32 v[80:81], v[22:23], v[70:71], v[80:81]
	v_pk_fma_f32 v[68:69], v[26:27], v[70:71], v[68:69]
	s_waitcnt lgkmcnt(1)
	v_pk_fma_f32 v[70:71], v[20:21], v[72:73], v[80:81]
	v_pk_fma_f32 v[68:69], v[18:19], v[72:73], v[68:69]
	v_pk_fma_f32 v[80:81], v[14:15], v[74:75], v[70:71]
	v_pk_fma_f32 v[72:73], v[16:17], v[74:75], v[68:69]
	ds_read_b128 v[68:71], v92 offset:19456
	s_waitcnt lgkmcnt(1)
	v_pk_fma_f32 v[74:75], v[12:13], v[76:77], v[80:81]
	v_pk_fma_f32 v[72:73], v[10:11], v[76:77], v[72:73]
	v_pk_fma_f32 v[74:75], v[6:7], v[78:79], v[74:75]
	v_pk_fma_f32 v[72:73], v[8:9], v[78:79], v[72:73]
	s_waitcnt lgkmcnt(0)
	v_pk_fma_f32 v[74:75], v[32:33], v[68:69], v[74:75]
	v_pk_fma_f32 v[68:69], v[30:31], v[68:69], v[72:73]
	v_pk_fma_f32 v[80:81], v[2:3], v[70:71], v[74:75]
	ds_read_b128 v[72:75], v92 offset:21504
	ds_read_b128 v[76:79], v92 offset:20480
	v_pk_fma_f32 v[70:71], v[4:5], v[70:71], v[68:69]
	v_pk_add_f32 v[68:69], v[80:81], v[80:81] op_sel:[0,1] op_sel_hi:[1,0]
	ds_read_b128 v[80:83], v92 offset:23552
	ds_read_b128 v[84:87], v92 offset:22528
	v_pk_add_f32 v[70:71], v[70:71], v[70:71] op_sel:[0,1] op_sel_hi:[1,0]
	s_waitcnt lgkmcnt(2)
	v_pk_fma_f32 v[88:89], v[24:25], v[76:77], 0 op_sel_hi:[1,1,0]
	v_pk_fma_f32 v[76:77], v[28:29], v[76:77], 0 op_sel_hi:[1,1,0]
	v_pk_fma_f32 v[88:89], v[22:23], v[78:79], v[88:89]
	v_pk_fma_f32 v[76:77], v[26:27], v[78:79], v[76:77]
	v_pk_fma_f32 v[78:79], v[20:21], v[72:73], v[88:89]
	v_pk_fma_f32 v[72:73], v[18:19], v[72:73], v[76:77]
	v_pk_fma_f32 v[78:79], v[14:15], v[74:75], v[78:79]
	v_pk_fma_f32 v[72:73], v[16:17], v[74:75], v[72:73]
	s_waitcnt lgkmcnt(0)
	v_pk_fma_f32 v[74:75], v[12:13], v[84:85], v[78:79]
	v_pk_fma_f32 v[72:73], v[10:11], v[84:85], v[72:73]
	v_pk_fma_f32 v[74:75], v[6:7], v[86:87], v[74:75]
	v_pk_fma_f32 v[72:73], v[8:9], v[86:87], v[72:73]
	v_pk_fma_f32 v[74:75], v[32:33], v[80:81], v[74:75]
	v_pk_fma_f32 v[72:73], v[30:31], v[80:81], v[72:73]
	v_pk_fma_f32 v[74:75], v[2:3], v[82:83], v[74:75]
	v_pk_fma_f32 v[76:77], v[4:5], v[82:83], v[72:73]
	v_pk_add_f32 v[72:73], v[74:75], v[74:75] op_sel:[0,1] op_sel_hi:[1,0]
	v_pk_add_f32 v[74:75], v[76:77], v[76:77] op_sel:[0,1] op_sel_hi:[1,0]
	ds_read_b128 v[76:79], v92 offset:24576
	ds_read_b128 v[80:83], v92 offset:25600
	ds_read_b128 v[84:87], v92 offset:26624
	s_waitcnt lgkmcnt(2)
	v_pk_fma_f32 v[88:89], v[24:25], v[76:77], 0 op_sel_hi:[1,1,0]
	v_pk_fma_f32 v[76:77], v[28:29], v[76:77], 0 op_sel_hi:[1,1,0]
	v_pk_fma_f32 v[88:89], v[22:23], v[78:79], v[88:89]
	v_pk_fma_f32 v[76:77], v[26:27], v[78:79], v[76:77]
	s_waitcnt lgkmcnt(1)
	v_pk_fma_f32 v[78:79], v[20:21], v[80:81], v[88:89]
	v_pk_fma_f32 v[76:77], v[18:19], v[80:81], v[76:77]
	v_pk_fma_f32 v[88:89], v[14:15], v[82:83], v[78:79]
	v_pk_fma_f32 v[80:81], v[16:17], v[82:83], v[76:77]
	ds_read_b128 v[76:79], v92 offset:27648
	s_waitcnt lgkmcnt(1)
	v_pk_fma_f32 v[82:83], v[12:13], v[84:85], v[88:89]
	v_pk_fma_f32 v[80:81], v[10:11], v[84:85], v[80:81]
	v_pk_fma_f32 v[82:83], v[6:7], v[86:87], v[82:83]
	v_pk_fma_f32 v[80:81], v[8:9], v[86:87], v[80:81]
	s_waitcnt lgkmcnt(0)
; __device__ void norm_phase(const Params& p, int layer, int which, int nrows, char* smem) {
;     ...
; #pragma unroll
;       for (int n = 0; n < 16; ++n) {
;         f32x2 a0 = {0.f, 0.f}, a1 = {0.f, 0.f};
; #pragma unroll
;         for (int i = 0; i < 4; ++i) {
;           const f32x4 wv = *(const f32x4*)(wgs + n * DM + i * 256 + lane * 4);
;           const f32x2 wlo = {wv[0], wv[1]}, whi = {wv[2], wv[3]};
;           a0 += (f32x2){v[0][i][0], v[0][i][1]} * wlo;
;           a0 += (f32x2){v[0][i][2], v[0][i][3]} * whi;
;           a1 += (f32x2){v[1][i][0], v[1][i][1]} * wlo;
;           a1 += (f32x2){v[1][i][2], v[1][i][3]} * whi;
;         }
;         a32[n] = a0[0] + a0[1];
;         a32[16 + n] = a1[0] + a1[1];
;         if ((n & 1) == 1) __builtin_amdgcn_sched_barrier(0);
;       }
	v_pk_fma_f32 v[82:83], v[32:33], v[76:77], v[82:83]
	v_pk_fma_f32 v[76:77], v[30:31], v[76:77], v[80:81]
	v_pk_fma_f32 v[88:89], v[2:3], v[78:79], v[82:83]
	ds_read_b128 v[80:83], v92 offset:29696
	ds_read_b128 v[84:87], v92 offset:28672
	v_pk_fma_f32 v[78:79], v[4:5], v[78:79], v[76:77]
	v_pk_add_f32 v[76:77], v[88:89], v[88:89] op_sel:[0,1] op_sel_hi:[1,0]
	ds_read_b128 v[88:91], v92 offset:31744
	ds_read_b128 v[98:101], v92 offset:30720
	v_pk_add_f32 v[78:79], v[78:79], v[78:79] op_sel:[0,1] op_sel_hi:[1,0]
	s_waitcnt lgkmcnt(2)
	v_pk_fma_f32 v[102:103], v[24:25], v[84:85], 0 op_sel_hi:[1,1,0]
	v_pk_fma_f32 v[84:85], v[28:29], v[84:85], 0 op_sel_hi:[1,1,0]
	v_pk_fma_f32 v[102:103], v[22:23], v[86:87], v[102:103]
	v_pk_fma_f32 v[84:85], v[26:27], v[86:87], v[84:85]
	v_pk_fma_f32 v[86:87], v[20:21], v[80:81], v[102:103]
	v_pk_fma_f32 v[80:81], v[18:19], v[80:81], v[84:85]
	v_pk_fma_f32 v[86:87], v[14:15], v[82:83], v[86:87]
	v_pk_fma_f32 v[80:81], v[16:17], v[82:83], v[80:81]
	s_waitcnt lgkmcnt(0)
	v_pk_fma_f32 v[82:83], v[12:13], v[98:99], v[86:87]
	v_pk_fma_f32 v[80:81], v[10:11], v[98:99], v[80:81]
	v_pk_fma_f32 v[82:83], v[6:7], v[100:101], v[82:83]
	v_pk_fma_f32 v[80:81], v[8:9], v[100:101], v[80:81]
	v_pk_fma_f32 v[82:83], v[32:33], v[88:89], v[82:83]
	v_pk_fma_f32 v[80:81], v[30:31], v[88:89], v[80:81]
	v_pk_fma_f32 v[82:83], v[2:3], v[90:91], v[82:83]
	v_pk_fma_f32 v[84:85], v[4:5], v[90:91], v[80:81]
	v_pk_add_f32 v[80:81], v[82:83], v[82:83] op_sel:[0,1] op_sel_hi:[1,0]
	v_pk_add_f32 v[82:83], v[84:85], v[84:85] op_sel:[0,1] op_sel_hi:[1,0]
	ds_read_b128 v[84:87], v92 offset:32768
	ds_read_b128 v[88:91], v92 offset:33792
	ds_read_b128 v[98:101], v92 offset:34816
	s_waitcnt lgkmcnt(2)
	v_pk_fma_f32 v[102:103], v[24:25], v[84:85], 0 op_sel_hi:[1,1,0]
	v_pk_fma_f32 v[84:85], v[28:29], v[84:85], 0 op_sel_hi:[1,1,0]
	v_pk_fma_f32 v[102:103], v[22:23], v[86:87], v[102:103]
	v_pk_fma_f32 v[84:85], v[26:27], v[86:87], v[84:85]
	s_waitcnt lgkmcnt(1)
	v_pk_fma_f32 v[86:87], v[20:21], v[88:89], v[102:103]
	v_pk_fma_f32 v[84:85], v[18:19], v[88:89], v[84:85]
	v_pk_fma_f32 v[102:103], v[14:15], v[90:91], v[86:87]
	v_pk_fma_f32 v[88:89], v[16:17], v[90:91], v[84:85]
	ds_read_b128 v[84:87], v92 offset:35840
	s_waitcnt lgkmcnt(1)
	v_pk_fma_f32 v[90:91], v[12:13], v[98:99], v[102:103]
	v_pk_fma_f32 v[88:89], v[10:11], v[98:99], v[88:89]
	v_pk_fma_f32 v[90:91], v[6:7], v[100:101], v[90:91]
	v_pk_fma_f32 v[88:89], v[8:9], v[100:101], v[88:89]
	s_waitcnt lgkmcnt(0)
	v_pk_fma_f32 v[90:91], v[32:33], v[84:85], v[90:91]
	v_pk_fma_f32 v[84:85], v[30:31], v[84:85], v[88:89]
	v_pk_fma_f32 v[102:103], v[2:3], v[86:87], v[90:91]
	ds_read_b128 v[88:91], v92 offset:37888
	ds_read_b128 v[98:101], v92 offset:36864
	v_pk_fma_f32 v[86:87], v[4:5], v[86:87], v[84:85]
	v_pk_add_f32 v[84:85], v[102:103], v[102:103] op_sel:[0,1] op_sel_hi:[1,0]
	ds_read_b128 v[102:105], v92 offset:39936
	ds_read_b128 v[106:109], v92 offset:38912
	v_pk_add_f32 v[86:87], v[86:87], v[86:87] op_sel:[0,1] op_sel_hi:[1,0]
	s_waitcnt lgkmcnt(2)
	v_pk_fma_f32 v[110:111], v[24:25], v[98:99], 0 op_sel_hi:[1,1,0]
	v_pk_fma_f32 v[98:99], v[28:29], v[98:99], 0 op_sel_hi:[1,1,0]
	v_pk_fma_f32 v[110:111], v[22:23], v[100:101], v[110:111]
	v_pk_fma_f32 v[98:99], v[26:27], v[100:101], v[98:99]
	v_pk_fma_f32 v[100:101], v[20:21], v[88:89], v[110:111]
	v_pk_fma_f32 v[88:89], v[18:19], v[88:89], v[98:99]
	v_pk_fma_f32 v[100:101], v[14:15], v[90:91], v[100:101]
	v_pk_fma_f32 v[88:89], v[16:17], v[90:91], v[88:89]
	s_waitcnt lgkmcnt(0)
	v_pk_fma_f32 v[90:91], v[12:13], v[106:107], v[100:101]
	v_pk_fma_f32 v[88:89], v[10:11], v[106:107], v[88:89]
	v_pk_fma_f32 v[90:91], v[6:7], v[108:109], v[90:91]
	v_pk_fma_f32 v[88:89], v[8:9], v[108:109], v[88:89]
	v_pk_fma_f32 v[90:91], v[32:33], v[102:103], v[90:91]
	v_pk_fma_f32 v[88:89], v[30:31], v[102:103], v[88:89]
	v_pk_fma_f32 v[90:91], v[2:3], v[104:105], v[90:91]
	v_pk_fma_f32 v[98:99], v[4:5], v[104:105], v[88:89]
	v_pk_add_f32 v[88:89], v[90:91], v[90:91] op_sel:[0,1] op_sel_hi:[1,0]
	v_pk_add_f32 v[90:91], v[98:99], v[98:99] op_sel:[0,1] op_sel_hi:[1,0]
	ds_read_b128 v[98:101], v92 offset:40960
	ds_read_b128 v[102:105], v92 offset:41984
	ds_read_b128 v[106:109], v92 offset:43008
	s_waitcnt lgkmcnt(2)
	v_pk_fma_f32 v[110:111], v[24:25], v[98:99], 0 op_sel_hi:[1,1,0]
	v_pk_fma_f32 v[98:99], v[28:29], v[98:99], 0 op_sel_hi:[1,1,0]
	v_pk_fma_f32 v[110:111], v[22:23], v[100:101], v[110:111]
	v_pk_fma_f32 v[98:99], v[26:27], v[100:101], v[98:99]
	s_waitcnt lgkmcnt(1)
	v_pk_fma_f32 v[100:101], v[20:21], v[102:103], v[110:111]
	v_pk_fma_f32 v[98:99], v[18:19], v[102:103], v[98:99]
	v_pk_fma_f32 v[110:111], v[14:15], v[104:105], v[100:101]
	v_pk_fma_f32 v[102:103], v[16:17], v[104:105], v[98:99]
	ds_read_b128 v[98:101], v92 offset:44032
	s_waitcnt lgkmcnt(1)
	v_pk_fma_f32 v[104:105], v[12:13], v[106:107], v[110:111]
	v_pk_fma_f32 v[102:103], v[10:11], v[106:107], v[102:103]
	v_pk_fma_f32 v[104:105], v[6:7], v[108:109], v[104:105]
	v_pk_fma_f32 v[102:103], v[8:9], v[108:109], v[102:103]
	s_waitcnt lgkmcnt(0)
	v_pk_fma_f32 v[104:105], v[32:33], v[98:99], v[104:105]
	v_pk_fma_f32 v[98:99], v[30:31], v[98:99], v[102:103]
	v_pk_fma_f32 v[106:107], v[2:3], v[100:101], v[104:105]
	v_pk_fma_f32 v[108:109], v[4:5], v[100:101], v[98:99]
	ds_read_b128 v[98:101], v92 offset:46080
	ds_read_b128 v[102:105], v92 offset:45056
	v_pk_add_f32 v[114:115], v[106:107], v[106:107] op_sel:[0,1] op_sel_hi:[1,0]
	v_pk_add_f32 v[116:117], v[108:109], v[108:109] op_sel:[0,1] op_sel_hi:[1,0]
	ds_read_b128 v[106:109], v92 offset:48128
	ds_read_b128 v[110:113], v92 offset:47104
	s_waitcnt lgkmcnt(2)
; __device__ void norm_phase(const Params& p, int layer, int which, int nrows, char* smem) {
;     ...
; #pragma unroll
;       for (int n = 0; n < 16; ++n) {
;         f32x2 a0 = {0.f, 0.f}, a1 = {0.f, 0.f};
; #pragma unroll
;         for (int i = 0; i < 4; ++i) {
;           const f32x4 wv = *(const f32x4*)(wgs + n * DM + i * 256 + lane * 4);
;           const f32x2 wlo = {wv[0], wv[1]}, whi = {wv[2], wv[3]};
;           a0 += (f32x2){v[0][i][0], v[0][i][1]} * wlo;
;           a0 += (f32x2){v[0][i][2], v[0][i][3]} * whi;
;           a1 += (f32x2){v[1][i][0], v[1][i][1]} * wlo;
;           a1 += (f32x2){v[1][i][2], v[1][i][3]} * whi;
;         }
;         a32[n] = a0[0] + a0[1];
;         a32[16 + n] = a1[0] + a1[1];
;         if ((n & 1) == 1) __builtin_amdgcn_sched_barrier(0);
;       }
	v_pk_fma_f32 v[118:119], v[24:25], v[102:103], 0 op_sel_hi:[1,1,0]
	v_pk_fma_f32 v[102:103], v[28:29], v[102:103], 0 op_sel_hi:[1,1,0]
	v_pk_fma_f32 v[118:119], v[22:23], v[104:105], v[118:119]
	v_pk_fma_f32 v[102:103], v[26:27], v[104:105], v[102:103]
	v_pk_fma_f32 v[104:105], v[20:21], v[98:99], v[118:119]
	v_pk_fma_f32 v[98:99], v[18:19], v[98:99], v[102:103]
	v_pk_fma_f32 v[104:105], v[14:15], v[100:101], v[104:105]
	v_pk_fma_f32 v[98:99], v[16:17], v[100:101], v[98:99]
	s_waitcnt lgkmcnt(0)
	v_pk_fma_f32 v[100:101], v[12:13], v[110:111], v[104:105]
	v_pk_fma_f32 v[98:99], v[10:11], v[110:111], v[98:99]
	v_pk_fma_f32 v[100:101], v[6:7], v[112:113], v[100:101]
	v_pk_fma_f32 v[98:99], v[8:9], v[112:113], v[98:99]
	v_pk_fma_f32 v[100:101], v[32:33], v[106:107], v[100:101]
	v_pk_fma_f32 v[98:99], v[30:31], v[106:107], v[98:99]
	v_pk_fma_f32 v[100:101], v[2:3], v[108:109], v[100:101]
	v_pk_fma_f32 v[98:99], v[4:5], v[108:109], v[98:99]
	v_pk_add_f32 v[118:119], v[100:101], v[100:101] op_sel:[0,1] op_sel_hi:[1,0]
	v_pk_add_f32 v[120:121], v[98:99], v[98:99] op_sel:[0,1] op_sel_hi:[1,0]
	ds_read_b128 v[98:101], v92 offset:49152
	ds_read_b128 v[102:105], v92 offset:50176
	ds_read_b128 v[106:109], v92 offset:51200
	s_waitcnt lgkmcnt(2)
	v_pk_fma_f32 v[110:111], v[24:25], v[98:99], 0 op_sel_hi:[1,1,0]
	v_pk_fma_f32 v[98:99], v[28:29], v[98:99], 0 op_sel_hi:[1,1,0]
	v_pk_fma_f32 v[110:111], v[22:23], v[100:101], v[110:111]
	v_pk_fma_f32 v[98:99], v[26:27], v[100:101], v[98:99]
	s_waitcnt lgkmcnt(1)
	v_pk_fma_f32 v[100:101], v[20:21], v[102:103], v[110:111]
	v_pk_fma_f32 v[98:99], v[18:19], v[102:103], v[98:99]
	v_pk_fma_f32 v[110:111], v[14:15], v[104:105], v[100:101]
	v_pk_fma_f32 v[102:103], v[16:17], v[104:105], v[98:99]
	ds_read_b128 v[98:101], v92 offset:52224
	s_waitcnt lgkmcnt(1)
	v_pk_fma_f32 v[104:105], v[12:13], v[106:107], v[110:111]
	v_pk_fma_f32 v[102:103], v[10:11], v[106:107], v[102:103]
	v_pk_fma_f32 v[104:105], v[6:7], v[108:109], v[104:105]
	v_pk_fma_f32 v[102:103], v[8:9], v[108:109], v[102:103]
	s_waitcnt lgkmcnt(0)
	v_pk_fma_f32 v[104:105], v[32:33], v[98:99], v[104:105]
	v_pk_fma_f32 v[98:99], v[30:31], v[98:99], v[102:103]
	v_pk_fma_f32 v[106:107], v[2:3], v[100:101], v[104:105]
	v_pk_fma_f32 v[108:109], v[4:5], v[100:101], v[98:99]
	ds_read_b128 v[98:101], v92 offset:54272
	ds_read_b128 v[102:105], v92 offset:53248
	v_pk_add_f32 v[122:123], v[106:107], v[106:107] op_sel:[0,1] op_sel_hi:[1,0]
	v_pk_add_f32 v[124:125], v[108:109], v[108:109] op_sel:[0,1] op_sel_hi:[1,0]
	ds_read_b128 v[106:109], v92 offset:56320
	ds_read_b128 v[110:113], v92 offset:55296
	s_waitcnt lgkmcnt(2)
	v_pk_fma_f32 v[126:127], v[24:25], v[102:103], 0 op_sel_hi:[1,1,0]
	v_pk_fma_f32 v[102:103], v[28:29], v[102:103], 0 op_sel_hi:[1,1,0]
	v_pk_fma_f32 v[126:127], v[22:23], v[104:105], v[126:127]
	v_pk_fma_f32 v[102:103], v[26:27], v[104:105], v[102:103]
	v_pk_fma_f32 v[104:105], v[20:21], v[98:99], v[126:127]
	v_pk_fma_f32 v[98:99], v[18:19], v[98:99], v[102:103]
	v_pk_fma_f32 v[104:105], v[14:15], v[100:101], v[104:105]
	v_pk_fma_f32 v[98:99], v[16:17], v[100:101], v[98:99]
	s_waitcnt lgkmcnt(0)
	v_pk_fma_f32 v[100:101], v[12:13], v[110:111], v[104:105]
	v_pk_fma_f32 v[98:99], v[10:11], v[110:111], v[98:99]
	v_pk_fma_f32 v[100:101], v[6:7], v[112:113], v[100:101]
	v_pk_fma_f32 v[98:99], v[8:9], v[112:113], v[98:99]
	v_pk_fma_f32 v[100:101], v[32:33], v[106:107], v[100:101]
	v_pk_fma_f32 v[98:99], v[30:31], v[106:107], v[98:99]
	v_pk_fma_f32 v[100:101], v[2:3], v[108:109], v[100:101]
	v_pk_fma_f32 v[98:99], v[4:5], v[108:109], v[98:99]
	v_pk_add_f32 v[126:127], v[100:101], v[100:101] op_sel:[0,1] op_sel_hi:[1,0]
	v_pk_add_f32 v[128:129], v[98:99], v[98:99] op_sel:[0,1] op_sel_hi:[1,0]
	ds_read_b128 v[98:101], v92 offset:57344
	ds_read_b128 v[102:105], v92 offset:58368
	ds_read_b128 v[106:109], v92 offset:59392
	s_waitcnt lgkmcnt(2)
	v_pk_fma_f32 v[110:111], v[24:25], v[98:99], 0 op_sel_hi:[1,1,0]
	v_pk_fma_f32 v[98:99], v[28:29], v[98:99], 0 op_sel_hi:[1,1,0]
	v_pk_fma_f32 v[110:111], v[22:23], v[100:101], v[110:111]
	v_pk_fma_f32 v[98:99], v[26:27], v[100:101], v[98:99]
	s_waitcnt lgkmcnt(1)
	v_pk_fma_f32 v[100:101], v[20:21], v[102:103], v[110:111]
	v_pk_fma_f32 v[98:99], v[18:19], v[102:103], v[98:99]
	v_pk_fma_f32 v[110:111], v[14:15], v[104:105], v[100:101]
	v_pk_fma_f32 v[102:103], v[16:17], v[104:105], v[98:99]
	ds_read_b128 v[98:101], v92 offset:60416
	s_waitcnt lgkmcnt(1)
	v_pk_fma_f32 v[104:105], v[12:13], v[106:107], v[110:111]
	v_pk_fma_f32 v[102:103], v[10:11], v[106:107], v[102:103]
	v_pk_fma_f32 v[104:105], v[6:7], v[108:109], v[104:105]
	v_pk_fma_f32 v[102:103], v[8:9], v[108:109], v[102:103]
	s_waitcnt lgkmcnt(0)
; DI float bfly32(float lo, float hi) { auto r = __builtin_amdgcn_permlane32_swap(__float_as_uint(lo), __float_as_uint(hi), false, false); return __uint_as_float(r[0]) + __uint_as_float(r[1]); }
; DI float bfly16(float lo, float hi) { auto r = __builtin_amdgcn_permlane16_swap(__float_as_uint(lo), __float_as_uint(hi), false, false); return __uint_as_float(r[0]) + __uint_as_float(r[1]); }
; __device__ void norm_phase(const Params& p, int layer, int which, int nrows, char* smem) {
;     ...
; #pragma unroll
;       for (int i = 0; i < 16; ++i) a32[i] = bfly32(a32[i], a32[i + 16]);
; #pragma unroll
;       for (int i = 0; i < 8; ++i) a32[i] = bfly16(a32[i], a32[i + 8]);
; #pragma unroll
;       for (int half = 4; half >= 1; half >>= 1) {
;         const int mask = half * 2;
;         const bool up = (lane & mask) != 0;
; #pragma unroll
;         for (int i = 0; i < half; ++i) {
;           const float send = up ? a32[i] : a32[i + half];
;           const float keep = up ? a32[i + half] : a32[i];
;           a32[i] = keep + __shfl_xor(send, mask);
;         }
;       }
;       const float tot = a32[0] + __shfl_xor(a32[0], 1);
;       if ((lane & 1) == 0) {
;         const int gi = (lane >> 1) & 15;
;         p.gates[(size_t)(row0 + (lane >> 5)) * 16 + gi] = tot + p.mlstm_b[layer * 16 + gi];
;       }
	v_pk_fma_f32 v[104:105], v[32:33], v[98:99], v[104:105]
	v_pk_fma_f32 v[98:99], v[30:31], v[98:99], v[102:103]
	v_pk_fma_f32 v[106:107], v[2:3], v[100:101], v[104:105]
	v_pk_fma_f32 v[108:109], v[4:5], v[100:101], v[98:99]
	ds_read_b128 v[98:101], v92 offset:62464
	ds_read_b128 v[102:105], v92 offset:61440
	v_pk_add_f32 v[130:131], v[106:107], v[106:107] op_sel:[0,1] op_sel_hi:[1,0]
	v_pk_add_f32 v[132:133], v[108:109], v[108:109] op_sel:[0,1] op_sel_hi:[1,0]
	ds_read_b128 v[106:109], v92 offset:64512
	ds_read_b128 v[110:113], v92 offset:63488
	s_waitcnt lgkmcnt(2)
	v_pk_fma_f32 v[24:25], v[24:25], v[102:103], 0 op_sel_hi:[1,1,0]
	s_nop 0
	v_pk_fma_f32 v[22:23], v[22:23], v[104:105], v[24:25]
	v_pk_fma_f32 v[24:25], v[28:29], v[102:103], 0 op_sel_hi:[1,1,0]
	v_pk_fma_f32 v[20:21], v[20:21], v[98:99], v[22:23]
	v_pk_fma_f32 v[24:25], v[26:27], v[104:105], v[24:25]
	v_pk_fma_f32 v[14:15], v[14:15], v[100:101], v[20:21]
	v_pk_fma_f32 v[18:19], v[18:19], v[98:99], v[24:25]
	s_waitcnt lgkmcnt(0)
	v_pk_fma_f32 v[12:13], v[12:13], v[110:111], v[14:15]
	v_pk_fma_f32 v[16:17], v[16:17], v[100:101], v[18:19]
	v_pk_fma_f32 v[6:7], v[6:7], v[112:113], v[12:13]
	v_pk_fma_f32 v[10:11], v[10:11], v[110:111], v[16:17]
	v_pk_fma_f32 v[6:7], v[32:33], v[106:107], v[6:7]
	v_pk_fma_f32 v[8:9], v[8:9], v[112:113], v[10:11]
	v_pk_fma_f32 v[2:3], v[2:3], v[108:109], v[6:7]
	v_pk_fma_f32 v[6:7], v[30:31], v[106:107], v[8:9]
	v_pk_add_f32 v[2:3], v[2:3], v[2:3] op_sel:[0,1] op_sel_hi:[1,0]
	v_pk_fma_f32 v[4:5], v[4:5], v[108:109], v[6:7]
	s_nop 0
	v_pk_add_f32 v[4:5], v[4:5], v[4:5] op_sel:[0,1] op_sel_hi:[1,0]
	v_permlane32_swap_b32_e32 v56, v58
	v_permlane32_swap_b32_e32 v60, v62
	v_permlane32_swap_b32_e32 v64, v66
	v_permlane32_swap_b32_e32 v68, v70
	v_permlane32_swap_b32_e32 v84, v86
	v_permlane32_swap_b32_e32 v114, v116
	v_permlane32_swap_b32_e32 v118, v120
	v_permlane32_swap_b32_e32 v122, v124
	v_add_f32_e32 v0, v56, v58
	v_add_f32_e32 v5, v60, v62
	v_add_f32_e32 v6, v64, v66
	v_add_f32_e32 v7, v68, v70
	v_permlane32_swap_b32_e32 v76, v78
	v_add_f32_e32 v11, v84, v86
	v_add_f32_e32 v13, v114, v116
	v_add_f32_e32 v14, v118, v120
	v_add_f32_e32 v15, v122, v124
	v_permlane32_swap_b32_e32 v130, v132
	v_add_f32_e32 v9, v76, v78
	v_add_f32_e32 v17, v130, v132
	v_permlane32_swap_b32_e32 v2, v4
	v_permlane16_swap_b32_e32 v0, v11
	v_permlane16_swap_b32_e32 v5, v13
	v_permlane16_swap_b32_e32 v6, v14
	v_permlane16_swap_b32_e32 v7, v15
	v_add_f32_e32 v2, v2, v4
	v_add_f32_e32 v0, v0, v11
	v_add_f32_e32 v4, v5, v13
	v_add_f32_e32 v5, v6, v14
	v_add_f32_e32 v6, v7, v15
	v_permlane16_swap_b32_e32 v9, v17
	v_add_f32_e32 v7, v9, v17
	v_cndmask_b32_e64 v9, v0, v6, s[36:37]
	v_permlane32_swap_b32_e32 v52, v54
	v_permlane32_swap_b32_e32 v72, v74
	v_permlane32_swap_b32_e32 v88, v90
	v_permlane32_swap_b32_e32 v126, v128
	ds_bpermute_b32 v9, v95, v9
	v_add_f32_e32 v3, v52, v54
	v_add_f32_e32 v8, v72, v74
	v_permlane32_swap_b32_e32 v80, v82
	v_add_f32_e32 v12, v88, v90
	v_add_f32_e32 v16, v126, v128
	v_add_f32_e32 v10, v80, v82
	v_permlane16_swap_b32_e32 v3, v12
	v_permlane16_swap_b32_e32 v8, v16
	v_permlane16_swap_b32_e32 v10, v2
	v_cndmask_b32_e64 v0, v6, v0, s[36:37]
	v_add_f32_e32 v6, v8, v16
	v_add_f32_e32 v3, v3, v12
	v_add_f32_e32 v2, v10, v2
	v_cndmask_b32_e64 v8, v3, v6, s[36:37]
	s_waitcnt lgkmcnt(0)
	v_add_f32_e32 v0, v0, v9
	v_cndmask_b32_e64 v3, v6, v3, s[36:37]
	ds_bpermute_b32 v6, v95, v8
	v_cndmask_b32_e64 v8, v4, v7, s[36:37]
	v_cndmask_b32_e64 v9, v5, v2, s[36:37]
	ds_bpermute_b32 v8, v95, v8
	ds_bpermute_b32 v9, v95, v9
	v_cndmask_b32_e64 v4, v7, v4, s[36:37]
	v_cndmask_b32_e64 v2, v2, v5, s[36:37]
	s_waitcnt lgkmcnt(2)
	v_add_f32_e32 v3, v3, v6
	s_waitcnt lgkmcnt(1)
	v_add_f32_e32 v4, v4, v8
	s_waitcnt lgkmcnt(0)
	v_add_f32_e32 v2, v2, v9
	v_cndmask_b32_e64 v5, v0, v4, s[40:41]
	v_cndmask_b32_e64 v6, v3, v2, s[40:41]
	ds_bpermute_b32 v5, v96, v5
	ds_bpermute_b32 v6, v96, v6
	v_cndmask_b32_e64 v0, v4, v0, s[40:41]
	v_cndmask_b32_e64 v2, v2, v3, s[40:41]
	s_waitcnt lgkmcnt(1)
	v_add_f32_e32 v0, v0, v5
	s_waitcnt lgkmcnt(0)
	v_add_f32_e32 v2, v2, v6
	v_cndmask_b32_e64 v3, v0, v2, s[42:43]
	ds_bpermute_b32 v3, v97, v3
	v_cndmask_b32_e64 v0, v2, v0, s[42:43]
	s_waitcnt lgkmcnt(0)
	v_add_f32_e32 v0, v0, v3
	ds_bpermute_b32 v2, v93, v0
	s_and_saveexec_b64 s[6:7], s[0:1]
	s_cbranch_execz .LBB0_74
	global_load_dword v4, v[40:41], off
	s_waitcnt lgkmcnt(0)
	v_add_f32_e32 v0, v0, v2
	v_add_u32_e32 v2, v94, v44
	v_ashrrev_i32_e32 v3, 31, v2
	v_lshlrev_b64 v[2:3], 6, v[2:3]
	v_lshl_add_u64 v[2:3], v[38:39], 0, v[2:3]
	s_waitcnt vmcnt(0)
	v_add_f32_e32 v0, v0, v4
	global_store_dword v[2:3], v0, off
	s_branch .LBB0_74

; __global__ void __launch_bounds__(NTHR) fwd_megakernel(Params p) {
;   extern __shared__ __attribute__((aligned(16))) char smem_raw[];
	.amdhsa_kernel _Z14fwd_megakernel6Params
		.amdhsa_group_segment_fixed_size 0
		.amdhsa_private_segment_fixed_size 0
		.amdhsa_kernarg_size 584
		.amdhsa_user_sgpr_count 2
		.amdhsa_user_sgpr_dispatch_ptr 0
		.amdhsa_user_sgpr_queue_ptr 0
		.amdhsa_user_sgpr_kernarg_segment_ptr 1
		.amdhsa_user_sgpr_dispatch_id 0
		.amdhsa_user_sgpr_kernarg_preload_length 0
		.amdhsa_user_sgpr_kernarg_preload_offset 0
		.amdhsa_user_sgpr_private_segment_size 0
		.amdhsa_uses_dynamic_stack 0
		.amdhsa_enable_private_segment 0
		.amdhsa_system_sgpr_workgroup_id_x 1
		.amdhsa_system_sgpr_workgroup_id_y 0
		.amdhsa_system_sgpr_workgroup_id_z 0
		.amdhsa_system_sgpr_workgroup_info 0
		.amdhsa_system_vgpr_workitem_id 2
		.amdhsa_next_free_vgpr 256
		.amdhsa_next_free_sgpr 102
		.amdhsa_accum_offset 256
		.amdhsa_reserve_vcc 1
		.amdhsa_float_round_mode_32 0
		.amdhsa_float_round_mode_16_64 0
		.amdhsa_float_denorm_mode_32 3
		.amdhsa_float_denorm_mode_16_64 3
		.amdhsa_dx10_clamp 1
		.amdhsa_ieee_mode 1
		.amdhsa_fp16_overflow 0
		.amdhsa_tg_split 0
		.amdhsa_exception_fp_ieee_invalid_op 0
		.amdhsa_exception_fp_denorm_src 0
		.amdhsa_exception_fp_ieee_div_zero 0
		.amdhsa_exception_fp_ieee_overflow 0
		.amdhsa_exception_fp_ieee_underflow 0
		.amdhsa_exception_fp_ieee_inexact 0
		.amdhsa_exception_int_div_zero 0
	.end_amdhsa_kernel

; __global__ void __launch_bounds__(NTHR) fwd_megakernel(Params p) {
;   extern __shared__ __attribute__((aligned(16))) char smem_raw[];
amdhsa.kernels:
  - .agpr_count:     0
    .args:
      - .offset:         0
        .size:           328
        .value_kind:     by_value
      - .offset:         328
        .size:           4
        .value_kind:     hidden_block_count_x
      - .offset:         332
        .size:           4
        .value_kind:     hidden_block_count_y
      - .offset:         336
        .size:           4
        .value_kind:     hidden_block_count_z
      - .offset:         340
        .size:           2
        .value_kind:     hidden_group_size_x
      - .offset:         342
        .size:           2
        .value_kind:     hidden_group_size_y
      - .offset:         344
        .size:           2
        .value_kind:     hidden_group_size_z
      - .offset:         346
        .size:           2
        .value_kind:     hidden_remainder_x
      - .offset:         348
        .size:           2
        .value_kind:     hidden_remainder_y
      - .offset:         350
        .size:           2
        .value_kind:     hidden_remainder_z
      - .offset:         368
        .size:           8
        .value_kind:     hidden_global_offset_x
      - .offset:         376
        .size:           8
        .value_kind:     hidden_global_offset_y
      - .offset:         384
        .size:           8
        .value_kind:     hidden_global_offset_z
      - .offset:         392
        .size:           2
        .value_kind:     hidden_grid_dims
      - .offset:         416
        .size:           8
        .value_kind:     hidden_multigrid_sync_arg
      - .offset:         448
        .size:           4
        .value_kind:     hidden_dynamic_lds_size
    .group_segment_fixed_size: 0
    .kernarg_segment_align: 8
    .kernarg_segment_size: 584
    .language:       OpenCL C
    .language_version:
      - 2
      - 0
    .max_flat_workgroup_size: 512
    .name:           _Z14fwd_megakernel6Params
    .private_segment_fixed_size: 0
    .sgpr_count:     108
    .sgpr_spill_count: 259
    .symbol:         _Z14fwd_megakernel6Params.kd
    .uniform_work_group_size: 1
    .uses_dynamic_stack: false
    .vgpr_count:     256
    .vgpr_spill_count: 0
    .wavefront_size: 64
